# v87 + dense QKV epilogue QK-norm row-sum exchanges via v_permlane16/32_swap
# speedup vs baseline: 1.0063x; 1.0011x over previous
.LBB0_773:
	s_lshl_b32 s4, s4, 10
	s_add_i32 s4, s4, 0
	s_lshl_b32 s6, s7, 8
	s_add_i32 s97, s4, s6
	s_add_i32 s97, s97, 0x20000
	v_mov_b32_e32 v179, v175
	v_mov_b32_e32 v157, v135
	v_lshl_add_u32 v156, v179, 2, s97
	ds_read_b32 v170, v156
	v_mov_b32_e32 v135, v131
	s_lshl_b32 s94, s7, 6
	s_lshl_b32 s66, s5, 8
	v_mov_b32_e32 v156, v130
	s_waitcnt lgkmcnt(0)
	v_pk_mul_f32 v[168:169], v[134:135], v[170:171] op_sel_hi:[1,0]
	v_mov_b32_e32 v134, v132
	v_mov_b32_e32 v135, v137
	v_pk_mul_f32 v[162:163], v[134:135], v[170:171] op_sel_hi:[1,0]
	v_mov_b32_e32 v135, v127
	v_mov_b32_e32 v127, v123
	v_mov_b32_e32 v137, v133
	v_pk_mul_f32 v[160:161], v[126:127], v[170:171] op_sel_hi:[1,0]
	v_mov_b32_e32 v126, v124
	v_mov_b32_e32 v127, v129
	v_mov_b32_e32 v129, v125
	s_add_i32 s4, s94, s66
	v_pk_mul_f32 v[166:167], v[156:157], v[170:171] op_sel_hi:[1,0]
	v_pk_mul_f32 v[164:165], v[136:137], v[170:171] op_sel_hi:[1,0]
	v_mov_b32_e32 v134, v122
	v_pk_mul_f32 v[136:137], v[126:127], v[170:171] op_sel_hi:[1,0]
	v_pk_mul_f32 v[156:157], v[128:129], v[170:171] op_sel_hi:[1,0]
	v_cndmask_b32_e64 v126, 0, 1, s[82:83]
	v_lshlrev_b32_e32 v177, 2, v178
	v_add_u32_e32 v180, s4, v179
	v_pk_mul_f32 v[158:159], v[134:135], v[170:171] op_sel_hi:[1,0]
	v_cmp_ne_u32_e64 s[40:41], 1, v126
	s_andn2_b64 vcc, exec, s[82:83]
	v_pk_mov_b32 v[134:135], v[136:137], v[156:157] op_sel:[1,0]
	s_cbranch_vccnz .LBB0_775
	v_pk_mul_f32 v[122:123], v[168:169], v[168:169]
	v_pk_mul_f32 v[124:125], v[166:167], v[166:167]
	v_pk_mul_f32 v[126:127], v[164:165], v[164:165]
	v_add_f32_e32 v122, v122, v125
	v_pk_mul_f32 v[128:129], v[162:163], v[162:163]
	v_add_f32_e32 v122, v126, v122
	v_add_f32_e32 v122, v129, v122
	v_add_f32_e32 v122, v124, v122
	v_add_f32_e32 v122, v123, v122
	v_add_f32_e32 v122, v128, v122
	v_add_f32_e32 v122, v127, v122
	v_fmac_f32_e32 v122, v160, v160
	v_pk_mul_f32 v[130:131], v[134:135], v[134:135]
	v_fmac_f32_e32 v122, v159, v159
	v_pk_mov_b32 v[132:133], v[160:161], v[158:159] op_sel:[1,0]
	v_add_f32_e32 v122, v131, v122
	v_pk_mul_f32 v[132:133], v[132:133], v[132:133]
	v_add_f32_e32 v122, v130, v122
	v_and_b32_e32 v124, 64, v238
	v_pk_mov_b32 v[134:135], v[156:157], v[136:137] op_sel:[1,0]
	v_add_f32_e32 v122, v133, v122
	v_xor_b32_e32 v123, 16, v238
	v_add_u32_e32 v124, 64, v124
	v_pk_mul_f32 v[134:135], v[134:135], v[134:135]
	v_add_f32_e32 v122, v132, v122
	v_cmp_lt_i32_e32 vcc, v123, v124
	v_add_f32_e32 v122, v135, v122
	v_add_f32_e32 v122, v134, v122
	v_cndmask_b32_e32 v123, v238, v123, vcc
	v_lshlrev_b32_e32 v123, 2, v123
	v_mov_b32_e32 v123, v122
	s_nop 1
	v_permlane16_swap_b32 v123, v122
	v_readlane_b32 s5, v253, 18
	s_waitcnt lgkmcnt(0)
	v_add_f32_e32 v122, v122, v123
	v_xor_b32_e32 v123, 32, v238
	v_cmp_lt_i32_e32 vcc, v123, v124
	s_nop 1
	v_cndmask_b32_e32 v123, v238, v123, vcc
	v_lshlrev_b32_e32 v123, 2, v123
	v_mov_b32_e32 v123, v122
	s_nop 1
	v_permlane32_swap_b32 v123, v122
	s_waitcnt lgkmcnt(0)
	v_add_f32_e32 v122, v122, v123
	v_fmamk_f32 v122, v122, 0x3c800000, v236
	v_rsq_f32_e32 v134, v122
	v_lshrrev_b32_e32 v122, 2, v180
	v_and_b32_e32 v122, 0x3f0, v122
	v_add_u32_e32 v122, v122, v177
	v_lshl_add_u32 v126, v122, 3, s5
	ds_read_b128 v[122:125], v126
	ds_read_b128 v[128:131], v126 offset:16
	v_pk_mul_f32 v[126:127], v[54:55], v[134:135] op_sel_hi:[1,0]
	v_pk_mul_f32 v[132:133], v[154:155], v[134:135] op_sel_hi:[1,0]
	v_pk_mul_f32 v[126:127], v[166:167], v[126:127]
	v_pk_mul_f32 v[132:133], v[168:169], v[132:133]
	s_waitcnt lgkmcnt(0)
	v_mov_b32_e32 v167, v124
	v_mov_b32_e32 v168, v122
	v_mov_b32_e32 v169, v125
	v_mov_b32_e32 v182, v124
	v_mov_b32_e32 v183, v122
	v_mov_b32_e32 v122, v125
	v_pk_mov_b32 v[124:125], v[132:133], v[126:127] op_sel:[1,0]
	v_mov_b32_e32 v166, v123
	v_pk_mul_f32 v[168:169], v[168:169], v[126:127]
	v_pk_mul_f32 v[122:123], v[122:123], v[124:125]
	v_pk_mul_f32 v[124:125], v[56:57], v[134:135] op_sel_hi:[1,0]
	v_pk_mov_b32 v[184:185], v[126:127], v[132:133] op_sel:[1,0]
	v_pk_fma_f32 v[126:127], v[166:167], v[132:133], v[168:169]
	v_pk_mul_f32 v[124:125], v[162:163], v[124:125]
	v_mov_b32_e32 v163, v130
	v_mov_b32_e32 v166, v130
	v_lshlrev_b32_e32 v130, 4, v179
	v_pk_mul_f32 v[132:133], v[152:153], v[134:135] op_sel_hi:[1,0]
	v_and_b32_e32 v130, 0x3f0, v130
	v_pk_mul_f32 v[132:133], v[164:165], v[132:133]
	v_mov_b32_e32 v164, v128
	v_mov_b32_e32 v165, v131
	v_add_u32_e32 v130, v130, v177
	v_mov_b32_e32 v162, v129
	v_pk_mul_f32 v[164:165], v[164:165], v[124:125]
	v_mov_b32_e32 v167, v128
	v_pk_mov_b32 v[168:169], v[124:125], v[132:133] op_sel:[1,0]
	v_mov_b32_e32 v128, v131
	v_pk_mov_b32 v[124:125], v[132:133], v[124:125] op_sel:[1,0]
	v_lshl_add_u32 v135, v130, 3, s5
	v_pk_mul_f32 v[124:125], v[128:129], v[124:125]
	v_pk_fma_f32 v[128:129], v[162:163], v[132:133], v[164:165]
	ds_read_b128 v[130:133], v135
	ds_read_b128 v[162:165], v135 offset:16
	v_pk_fma_f32 v[124:125], v[166:167], v[168:169], v[124:125] neg_lo:[0,0,1] neg_hi:[0,0,1]
	v_pk_mul_f32 v[166:167], v[46:47], v[134:135] op_sel_hi:[1,0]
	v_pk_fma_f32 v[122:123], v[182:183], v[184:185], v[122:123] neg_lo:[0,0,1] neg_hi:[0,0,1]
	v_pk_mul_f32 v[158:159], v[158:159], v[166:167]
	v_pk_mul_f32 v[166:167], v[150:151], v[134:135] op_sel_hi:[1,0]
	s_waitcnt lgkmcnt(0)
	v_mov_b32_e32 v168, v130
	v_pk_mul_f32 v[160:161], v[160:161], v[166:167]
	v_mov_b32_e32 v169, v133
	v_mov_b32_e32 v167, v132
	v_pk_mul_f32 v[168:169], v[168:169], v[158:159]
	v_mov_b32_e32 v182, v132
	v_mov_b32_e32 v183, v130
	v_pk_mov_b32 v[184:185], v[158:159], v[160:161] op_sel:[1,0]
	v_mov_b32_e32 v130, v133
	v_pk_mov_b32 v[132:133], v[160:161], v[158:159] op_sel:[1,0]
	v_pk_mul_f32 v[158:159], v[48:49], v[134:135] op_sel_hi:[1,0]
	v_pk_mul_f32 v[134:135], v[148:149], v[134:135] op_sel_hi:[1,0]
	v_mov_b32_e32 v166, v131
	v_pk_mul_f32 v[130:131], v[130:131], v[132:133]
	v_pk_mul_f32 v[136:137], v[136:137], v[158:159]
	v_pk_mul_f32 v[156:157], v[156:157], v[134:135]
	v_mov_b32_e32 v134, v162
	v_mov_b32_e32 v135, v165
	v_pk_fma_f32 v[132:133], v[182:183], v[184:185], v[130:131] neg_lo:[0,0,1] neg_hi:[0,0,1]
	v_pk_fma_f32 v[130:131], v[166:167], v[160:161], v[168:169]
	v_pk_mul_f32 v[160:161], v[134:135], v[136:137]
	v_mov_b32_e32 v135, v162
	v_pk_mov_b32 v[166:167], v[136:137], v[156:157] op_sel:[1,0]
	v_mov_b32_e32 v162, v165
	v_pk_mov_b32 v[136:137], v[156:157], v[136:137] op_sel:[1,0]
	v_mov_b32_e32 v158, v163
	v_mov_b32_e32 v159, v164
	v_mov_b32_e32 v134, v164
	v_pk_mul_f32 v[136:137], v[162:163], v[136:137]
	s_nop 0
	v_pk_fma_f32 v[134:135], v[134:135], v[166:167], v[136:137] neg_lo:[0,0,1] neg_hi:[0,0,1]
	v_pk_fma_f32 v[136:137], v[158:159], v[156:157], v[160:161]
	v_cndmask_b32_e64 v156, 0, 1, s[44:45]
	v_cmp_ne_u32_e64 s[42:43], 1, v156
	s_andn2_b64 vcc, exec, s[44:45]
	s_cbranch_vccz .LBB0_776
	s_branch .LBB0_777

.LBB0_781:
	v_mov_b32_e32 v137, v175
	s_nop 0
	v_mov_b32_e32 v123, v119
	v_lshl_add_u32 v122, v137, 2, s97
	ds_read_b32 v136, v122 offset:64
	v_mov_b32_e32 v119, v115
	v_mov_b32_e32 v122, v114
	v_add3_u32 v158, v137, s94, 16
	v_add_u32_e32 v157, s66, v158
	s_waitcnt lgkmcnt(0)
	v_pk_mul_f32 v[134:135], v[118:119], v[136:137] op_sel_hi:[1,0]
	v_mov_b32_e32 v118, v116
	v_mov_b32_e32 v119, v121
	v_pk_mul_f32 v[128:129], v[118:119], v[136:137] op_sel_hi:[1,0]
	v_mov_b32_e32 v119, v111
	v_mov_b32_e32 v111, v107
	v_mov_b32_e32 v121, v117
	v_pk_mul_f32 v[126:127], v[110:111], v[136:137] op_sel_hi:[1,0]
	v_mov_b32_e32 v110, v108
	v_mov_b32_e32 v111, v113
	v_mov_b32_e32 v113, v109
	v_pk_mul_f32 v[132:133], v[122:123], v[136:137] op_sel_hi:[1,0]
	v_pk_mul_f32 v[130:131], v[120:121], v[136:137] op_sel_hi:[1,0]
	v_mov_b32_e32 v118, v106
	v_pk_mul_f32 v[120:121], v[110:111], v[136:137] op_sel_hi:[1,0]
	v_pk_mul_f32 v[122:123], v[112:113], v[136:137] op_sel_hi:[1,0]
	v_pk_mul_f32 v[124:125], v[118:119], v[136:137] op_sel_hi:[1,0]
	s_and_b64 vcc, exec, s[40:41]
	v_pk_mov_b32 v[118:119], v[120:121], v[122:123] op_sel:[1,0]
	s_cbranch_vccnz .LBB0_783
	v_pk_mul_f32 v[106:107], v[134:135], v[134:135]
	v_pk_mul_f32 v[108:109], v[132:133], v[132:133]
	v_pk_mul_f32 v[110:111], v[130:131], v[130:131]
	v_add_f32_e32 v106, v106, v109
	v_pk_mul_f32 v[112:113], v[128:129], v[128:129]
	v_add_f32_e32 v106, v110, v106
	v_add_f32_e32 v106, v113, v106
	v_add_f32_e32 v106, v108, v106
	v_add_f32_e32 v106, v107, v106
	v_add_f32_e32 v106, v112, v106
	v_add_f32_e32 v106, v111, v106
	v_fmac_f32_e32 v106, v126, v126
	v_pk_mul_f32 v[114:115], v[118:119], v[118:119]
	v_fmac_f32_e32 v106, v125, v125
	v_pk_mov_b32 v[116:117], v[126:127], v[124:125] op_sel:[1,0]
	v_add_f32_e32 v106, v115, v106
	v_pk_mul_f32 v[116:117], v[116:117], v[116:117]
	v_add_f32_e32 v106, v114, v106
	v_and_b32_e32 v108, 64, v238
	v_pk_mov_b32 v[118:119], v[122:123], v[120:121] op_sel:[1,0]
	v_add_f32_e32 v106, v117, v106
	v_xor_b32_e32 v107, 16, v238
	v_add_u32_e32 v108, 64, v108
	v_pk_mul_f32 v[118:119], v[118:119], v[118:119]
	v_add_f32_e32 v106, v116, v106
	v_cmp_lt_i32_e32 vcc, v107, v108
	v_add_f32_e32 v106, v119, v106
	v_add_f32_e32 v106, v118, v106
	v_cndmask_b32_e32 v107, v238, v107, vcc
	v_lshlrev_b32_e32 v107, 2, v107
	v_mov_b32_e32 v107, v106
	s_nop 1
	v_permlane16_swap_b32 v107, v106
	v_readlane_b32 s5, v253, 18
	s_waitcnt lgkmcnt(0)
	v_add_f32_e32 v106, v106, v107
	v_xor_b32_e32 v107, 32, v238
	v_cmp_lt_i32_e32 vcc, v107, v108
	s_nop 1
	v_cndmask_b32_e32 v107, v238, v107, vcc
	v_lshlrev_b32_e32 v107, 2, v107
	v_mov_b32_e32 v107, v106
	s_nop 1
	v_permlane32_swap_b32 v107, v106
	s_waitcnt lgkmcnt(0)
	v_add_f32_e32 v106, v106, v107
	v_fmamk_f32 v106, v106, 0x3c800000, v236
	v_rsq_f32_e32 v118, v106
	v_lshrrev_b32_e32 v106, 2, v157
	v_and_b32_e32 v106, 0x3f0, v106
	v_add_u32_e32 v106, v106, v177
	v_lshl_add_u32 v110, v106, 3, s5
	ds_read_b128 v[106:109], v110
	ds_read_b128 v[112:115], v110 offset:16
	v_pk_mul_f32 v[110:111], v[54:55], v[118:119] op_sel_hi:[1,0]
	v_pk_mul_f32 v[116:117], v[154:155], v[118:119] op_sel_hi:[1,0]
	v_pk_mul_f32 v[110:111], v[132:133], v[110:111]
	v_pk_mul_f32 v[116:117], v[134:135], v[116:117]
	s_waitcnt lgkmcnt(0)
	v_mov_b32_e32 v133, v108
	v_mov_b32_e32 v134, v106
	v_mov_b32_e32 v135, v109
	v_mov_b32_e32 v160, v108
	v_mov_b32_e32 v161, v106
	v_mov_b32_e32 v106, v109
	v_pk_mov_b32 v[108:109], v[116:117], v[110:111] op_sel:[1,0]
	v_mov_b32_e32 v132, v107
	v_pk_mul_f32 v[134:135], v[134:135], v[110:111]
	v_pk_mul_f32 v[106:107], v[106:107], v[108:109]
	v_pk_mul_f32 v[108:109], v[56:57], v[118:119] op_sel_hi:[1,0]
	v_pk_mov_b32 v[162:163], v[110:111], v[116:117] op_sel:[1,0]
	v_pk_fma_f32 v[110:111], v[132:133], v[116:117], v[134:135]
	v_pk_mul_f32 v[108:109], v[128:129], v[108:109]
	v_mov_b32_e32 v129, v114
	v_mov_b32_e32 v132, v114
	v_lshlrev_b32_e32 v114, 4, v158
	v_pk_mul_f32 v[116:117], v[152:153], v[118:119] op_sel_hi:[1,0]
	v_and_b32_e32 v114, 0x3f0, v114
	v_pk_mul_f32 v[116:117], v[130:131], v[116:117]
	v_mov_b32_e32 v130, v112
	v_mov_b32_e32 v131, v115
	v_add_u32_e32 v114, v114, v177
	v_mov_b32_e32 v128, v113
	v_pk_mul_f32 v[130:131], v[130:131], v[108:109]
	v_mov_b32_e32 v133, v112
	v_pk_mov_b32 v[134:135], v[108:109], v[116:117] op_sel:[1,0]
	v_mov_b32_e32 v112, v115
	v_pk_mov_b32 v[108:109], v[116:117], v[108:109] op_sel:[1,0]
	v_lshl_add_u32 v119, v114, 3, s5
	v_pk_mul_f32 v[108:109], v[112:113], v[108:109]
	v_pk_fma_f32 v[112:113], v[128:129], v[116:117], v[130:131]
	ds_read_b128 v[114:117], v119
	ds_read_b128 v[128:131], v119 offset:16
	v_pk_fma_f32 v[108:109], v[132:133], v[134:135], v[108:109] neg_lo:[0,0,1] neg_hi:[0,0,1]
	v_pk_mul_f32 v[132:133], v[46:47], v[118:119] op_sel_hi:[1,0]
	v_pk_fma_f32 v[106:107], v[160:161], v[162:163], v[106:107] neg_lo:[0,0,1] neg_hi:[0,0,1]
	v_pk_mul_f32 v[124:125], v[124:125], v[132:133]
	v_pk_mul_f32 v[132:133], v[150:151], v[118:119] op_sel_hi:[1,0]
	s_waitcnt lgkmcnt(0)
	v_mov_b32_e32 v134, v114
	v_pk_mul_f32 v[126:127], v[126:127], v[132:133]
	v_mov_b32_e32 v135, v117
	v_mov_b32_e32 v133, v116
	v_pk_mul_f32 v[134:135], v[134:135], v[124:125]
	v_mov_b32_e32 v158, v116
	v_mov_b32_e32 v159, v114
	v_pk_mov_b32 v[160:161], v[124:125], v[126:127] op_sel:[1,0]
	v_mov_b32_e32 v114, v117
	v_pk_mov_b32 v[116:117], v[126:127], v[124:125] op_sel:[1,0]
	v_pk_mul_f32 v[124:125], v[48:49], v[118:119] op_sel_hi:[1,0]
	v_pk_mul_f32 v[118:119], v[148:149], v[118:119] op_sel_hi:[1,0]
	v_mov_b32_e32 v132, v115
	v_pk_mul_f32 v[114:115], v[114:115], v[116:117]
	v_pk_mul_f32 v[120:121], v[120:121], v[124:125]
	v_pk_mul_f32 v[122:123], v[122:123], v[118:119]
	v_mov_b32_e32 v118, v128
	v_mov_b32_e32 v119, v131
	v_pk_fma_f32 v[116:117], v[158:159], v[160:161], v[114:115] neg_lo:[0,0,1] neg_hi:[0,0,1]
	v_pk_fma_f32 v[114:115], v[132:133], v[126:127], v[134:135]
	v_pk_mul_f32 v[126:127], v[118:119], v[120:121]
	v_mov_b32_e32 v119, v128
	v_pk_mov_b32 v[132:133], v[120:121], v[122:123] op_sel:[1,0]
	v_mov_b32_e32 v128, v131
	v_pk_mov_b32 v[120:121], v[122:123], v[120:121] op_sel:[1,0]
	v_mov_b32_e32 v124, v129
	v_mov_b32_e32 v125, v130
	v_mov_b32_e32 v118, v130
	v_pk_mul_f32 v[120:121], v[128:129], v[120:121]
	s_nop 0
	v_pk_fma_f32 v[118:119], v[118:119], v[132:133], v[120:121] neg_lo:[0,0,1] neg_hi:[0,0,1]
	v_pk_fma_f32 v[120:121], v[124:125], v[122:123], v[126:127]
	s_and_b64 vcc, exec, s[42:43]
	s_cbranch_vccz .LBB0_784
	s_branch .LBB0_785

.LBB0_789:
	v_mov_b32_e32 v121, v175
	s_nop 0
	v_mov_b32_e32 v107, v103
	v_lshl_add_u32 v106, v121, 2, s97
	ds_read_b32 v120, v106 offset:128
	v_mov_b32_e32 v103, v99
	v_mov_b32_e32 v106, v98
	v_add3_u32 v123, v121, s94, 32
	v_add_u32_e32 v122, s66, v123
	s_waitcnt lgkmcnt(0)
	v_pk_mul_f32 v[118:119], v[102:103], v[120:121] op_sel_hi:[1,0]
	v_mov_b32_e32 v102, v100
	v_mov_b32_e32 v103, v105
	v_pk_mul_f32 v[112:113], v[102:103], v[120:121] op_sel_hi:[1,0]
	v_mov_b32_e32 v103, v95
	v_mov_b32_e32 v95, v91
	v_mov_b32_e32 v105, v101
	v_pk_mul_f32 v[110:111], v[94:95], v[120:121] op_sel_hi:[1,0]
	v_mov_b32_e32 v94, v92
	v_mov_b32_e32 v95, v97
	v_mov_b32_e32 v97, v93
	v_pk_mul_f32 v[116:117], v[106:107], v[120:121] op_sel_hi:[1,0]
	v_pk_mul_f32 v[114:115], v[104:105], v[120:121] op_sel_hi:[1,0]
	v_mov_b32_e32 v102, v90
	v_pk_mul_f32 v[104:105], v[94:95], v[120:121] op_sel_hi:[1,0]
	v_pk_mul_f32 v[106:107], v[96:97], v[120:121] op_sel_hi:[1,0]
	v_pk_mul_f32 v[108:109], v[102:103], v[120:121] op_sel_hi:[1,0]
	s_and_b64 vcc, exec, s[40:41]
	v_pk_mov_b32 v[102:103], v[104:105], v[106:107] op_sel:[1,0]
	s_cbranch_vccnz .LBB0_791
	v_pk_mul_f32 v[90:91], v[118:119], v[118:119]
	v_pk_mul_f32 v[92:93], v[116:117], v[116:117]
	v_pk_mul_f32 v[94:95], v[114:115], v[114:115]
	v_add_f32_e32 v90, v90, v93
	v_pk_mul_f32 v[96:97], v[112:113], v[112:113]
	v_add_f32_e32 v90, v94, v90
	v_add_f32_e32 v90, v97, v90
	v_add_f32_e32 v90, v92, v90
	v_add_f32_e32 v90, v91, v90
	v_add_f32_e32 v90, v96, v90
	v_add_f32_e32 v90, v95, v90
	v_fmac_f32_e32 v90, v110, v110
	v_pk_mul_f32 v[98:99], v[102:103], v[102:103]
	v_fmac_f32_e32 v90, v109, v109
	v_pk_mov_b32 v[100:101], v[110:111], v[108:109] op_sel:[1,0]
	v_add_f32_e32 v90, v99, v90
	v_pk_mul_f32 v[100:101], v[100:101], v[100:101]
	v_add_f32_e32 v90, v98, v90
	v_and_b32_e32 v92, 64, v238
	v_pk_mov_b32 v[102:103], v[106:107], v[104:105] op_sel:[1,0]
	v_add_f32_e32 v90, v101, v90
	v_xor_b32_e32 v91, 16, v238
	v_add_u32_e32 v92, 64, v92
	v_pk_mul_f32 v[102:103], v[102:103], v[102:103]
	v_add_f32_e32 v90, v100, v90
	v_cmp_lt_i32_e32 vcc, v91, v92
	v_add_f32_e32 v90, v103, v90
	v_add_f32_e32 v90, v102, v90
	v_cndmask_b32_e32 v91, v238, v91, vcc
	v_lshlrev_b32_e32 v91, 2, v91
	v_mov_b32_e32 v91, v90
	s_nop 1
	v_permlane16_swap_b32 v91, v90
	v_readlane_b32 s5, v253, 18
	s_waitcnt lgkmcnt(0)
	v_add_f32_e32 v90, v90, v91
	v_xor_b32_e32 v91, 32, v238
	v_cmp_lt_i32_e32 vcc, v91, v92
	s_nop 1
	v_cndmask_b32_e32 v91, v238, v91, vcc
	v_lshlrev_b32_e32 v91, 2, v91
	v_mov_b32_e32 v91, v90
	s_nop 1
	v_permlane32_swap_b32 v91, v90
	s_waitcnt lgkmcnt(0)
	v_add_f32_e32 v90, v90, v91
	v_fmamk_f32 v90, v90, 0x3c800000, v236
	v_rsq_f32_e32 v102, v90
	v_lshrrev_b32_e32 v90, 2, v122
	v_and_b32_e32 v90, 0x3f0, v90
	v_add_u32_e32 v90, v90, v177
	v_lshl_add_u32 v94, v90, 3, s5
	ds_read_b128 v[90:93], v94
	ds_read_b128 v[96:99], v94 offset:16
	v_pk_mul_f32 v[94:95], v[54:55], v[102:103] op_sel_hi:[1,0]
	v_pk_mul_f32 v[100:101], v[154:155], v[102:103] op_sel_hi:[1,0]
	v_pk_mul_f32 v[94:95], v[116:117], v[94:95]
	v_pk_mul_f32 v[100:101], v[118:119], v[100:101]
	s_waitcnt lgkmcnt(0)
	v_mov_b32_e32 v117, v92
	v_mov_b32_e32 v118, v90
	v_mov_b32_e32 v119, v93
	v_mov_b32_e32 v124, v92
	v_mov_b32_e32 v125, v90
	v_mov_b32_e32 v90, v93
	v_pk_mov_b32 v[92:93], v[100:101], v[94:95] op_sel:[1,0]
	v_mov_b32_e32 v116, v91
	v_pk_mul_f32 v[118:119], v[118:119], v[94:95]
	v_pk_mul_f32 v[90:91], v[90:91], v[92:93]
	v_pk_mul_f32 v[92:93], v[56:57], v[102:103] op_sel_hi:[1,0]
	v_pk_mov_b32 v[126:127], v[94:95], v[100:101] op_sel:[1,0]
	v_pk_fma_f32 v[94:95], v[116:117], v[100:101], v[118:119]
	v_pk_mul_f32 v[92:93], v[112:113], v[92:93]
	v_mov_b32_e32 v113, v98
	v_mov_b32_e32 v116, v98
	v_lshlrev_b32_e32 v98, 4, v123
	v_pk_mul_f32 v[100:101], v[152:153], v[102:103] op_sel_hi:[1,0]
	v_and_b32_e32 v98, 0x3f0, v98
	v_pk_mul_f32 v[100:101], v[114:115], v[100:101]
	v_mov_b32_e32 v114, v96
	v_mov_b32_e32 v115, v99
	v_add_u32_e32 v98, v98, v177
	v_mov_b32_e32 v112, v97
	v_pk_mul_f32 v[114:115], v[114:115], v[92:93]
	v_mov_b32_e32 v117, v96
	v_pk_mov_b32 v[118:119], v[92:93], v[100:101] op_sel:[1,0]
	v_mov_b32_e32 v96, v99
	v_pk_mov_b32 v[92:93], v[100:101], v[92:93] op_sel:[1,0]
	v_lshl_add_u32 v103, v98, 3, s5
	v_pk_mul_f32 v[92:93], v[96:97], v[92:93]
	v_pk_fma_f32 v[96:97], v[112:113], v[100:101], v[114:115]
	ds_read_b128 v[98:101], v103
	ds_read_b128 v[112:115], v103 offset:16
	v_pk_fma_f32 v[92:93], v[116:117], v[118:119], v[92:93] neg_lo:[0,0,1] neg_hi:[0,0,1]
	v_pk_mul_f32 v[116:117], v[46:47], v[102:103] op_sel_hi:[1,0]
	v_pk_fma_f32 v[90:91], v[124:125], v[126:127], v[90:91] neg_lo:[0,0,1] neg_hi:[0,0,1]
	v_pk_mul_f32 v[108:109], v[108:109], v[116:117]
	v_pk_mul_f32 v[116:117], v[150:151], v[102:103] op_sel_hi:[1,0]
	s_waitcnt lgkmcnt(0)
	v_mov_b32_e32 v118, v98
	v_pk_mul_f32 v[110:111], v[110:111], v[116:117]
	v_mov_b32_e32 v119, v101
	v_mov_b32_e32 v117, v100
	v_pk_mul_f32 v[118:119], v[118:119], v[108:109]
	v_mov_b32_e32 v124, v100
	v_mov_b32_e32 v125, v98
	v_pk_mov_b32 v[126:127], v[108:109], v[110:111] op_sel:[1,0]
	v_mov_b32_e32 v98, v101
	v_pk_mov_b32 v[100:101], v[110:111], v[108:109] op_sel:[1,0]
	v_pk_mul_f32 v[108:109], v[48:49], v[102:103] op_sel_hi:[1,0]
	v_pk_mul_f32 v[102:103], v[148:149], v[102:103] op_sel_hi:[1,0]
	v_mov_b32_e32 v116, v99
	v_pk_mul_f32 v[98:99], v[98:99], v[100:101]
	v_pk_mul_f32 v[104:105], v[104:105], v[108:109]
	v_pk_mul_f32 v[106:107], v[106:107], v[102:103]
	v_mov_b32_e32 v102, v112
	v_mov_b32_e32 v103, v115
	v_pk_fma_f32 v[100:101], v[124:125], v[126:127], v[98:99] neg_lo:[0,0,1] neg_hi:[0,0,1]
	v_pk_fma_f32 v[98:99], v[116:117], v[110:111], v[118:119]
	v_pk_mul_f32 v[110:111], v[102:103], v[104:105]
	v_mov_b32_e32 v103, v112
	v_pk_mov_b32 v[116:117], v[104:105], v[106:107] op_sel:[1,0]
	v_mov_b32_e32 v112, v115
	v_pk_mov_b32 v[104:105], v[106:107], v[104:105] op_sel:[1,0]
	v_mov_b32_e32 v108, v113
	v_mov_b32_e32 v109, v114
	v_mov_b32_e32 v102, v114
	v_pk_mul_f32 v[104:105], v[112:113], v[104:105]
	s_nop 0
	v_pk_fma_f32 v[102:103], v[102:103], v[116:117], v[104:105] neg_lo:[0,0,1] neg_hi:[0,0,1]
	v_pk_fma_f32 v[104:105], v[108:109], v[106:107], v[110:111]
	s_and_b64 vcc, exec, s[42:43]
	s_cbranch_vccz .LBB0_792
	s_branch .LBB0_793

.LBB0_797:
	v_mov_b32_e32 v105, v175
	s_nop 0
	v_mov_b32_e32 v91, v87
	v_lshl_add_u32 v90, v105, 2, s97
	ds_read_b32 v104, v90 offset:192
	v_mov_b32_e32 v87, v83
	v_mov_b32_e32 v90, v82
	v_add3_u32 v107, v105, s94, 48
	v_add_u32_e32 v106, s66, v107
	s_waitcnt lgkmcnt(0)
	v_pk_mul_f32 v[102:103], v[86:87], v[104:105] op_sel_hi:[1,0]
	v_mov_b32_e32 v86, v84
	v_mov_b32_e32 v87, v89
	v_pk_mul_f32 v[96:97], v[86:87], v[104:105] op_sel_hi:[1,0]
	v_mov_b32_e32 v87, v79
	v_mov_b32_e32 v79, v75
	v_mov_b32_e32 v89, v85
	v_pk_mul_f32 v[94:95], v[78:79], v[104:105] op_sel_hi:[1,0]
	v_mov_b32_e32 v78, v76
	v_mov_b32_e32 v79, v81
	v_mov_b32_e32 v81, v77
	v_pk_mul_f32 v[100:101], v[90:91], v[104:105] op_sel_hi:[1,0]
	v_pk_mul_f32 v[98:99], v[88:89], v[104:105] op_sel_hi:[1,0]
	v_mov_b32_e32 v86, v74
	v_pk_mul_f32 v[88:89], v[78:79], v[104:105] op_sel_hi:[1,0]
	v_pk_mul_f32 v[90:91], v[80:81], v[104:105] op_sel_hi:[1,0]
	v_pk_mul_f32 v[92:93], v[86:87], v[104:105] op_sel_hi:[1,0]
	s_and_b64 vcc, exec, s[40:41]
	v_pk_mov_b32 v[86:87], v[88:89], v[90:91] op_sel:[1,0]
	s_cbranch_vccnz .LBB0_799
	v_pk_mul_f32 v[74:75], v[102:103], v[102:103]
	v_pk_mul_f32 v[76:77], v[100:101], v[100:101]
	v_pk_mul_f32 v[78:79], v[98:99], v[98:99]
	v_add_f32_e32 v74, v74, v77
	v_pk_mul_f32 v[80:81], v[96:97], v[96:97]
	v_add_f32_e32 v74, v78, v74
	v_add_f32_e32 v74, v81, v74
	v_add_f32_e32 v74, v76, v74
	v_add_f32_e32 v74, v75, v74
	v_add_f32_e32 v74, v80, v74
	v_add_f32_e32 v74, v79, v74
	v_fmac_f32_e32 v74, v94, v94
	v_pk_mul_f32 v[82:83], v[86:87], v[86:87]
	v_fmac_f32_e32 v74, v93, v93
	v_pk_mov_b32 v[84:85], v[94:95], v[92:93] op_sel:[1,0]
	v_add_f32_e32 v74, v83, v74
	v_pk_mul_f32 v[84:85], v[84:85], v[84:85]
	v_add_f32_e32 v74, v82, v74
	v_and_b32_e32 v76, 64, v238
	v_pk_mov_b32 v[86:87], v[90:91], v[88:89] op_sel:[1,0]
	v_add_f32_e32 v74, v85, v74
	v_xor_b32_e32 v75, 16, v238
	v_add_u32_e32 v76, 64, v76
	v_pk_mul_f32 v[86:87], v[86:87], v[86:87]
	v_add_f32_e32 v74, v84, v74
	v_cmp_lt_i32_e32 vcc, v75, v76
	v_add_f32_e32 v74, v87, v74
	v_add_f32_e32 v74, v86, v74
	v_cndmask_b32_e32 v75, v238, v75, vcc
	v_lshlrev_b32_e32 v75, 2, v75
	v_mov_b32_e32 v75, v74
	s_nop 1
	v_permlane16_swap_b32 v75, v74
	v_readlane_b32 s5, v253, 18
	s_waitcnt lgkmcnt(0)
	v_add_f32_e32 v74, v74, v75
	v_xor_b32_e32 v75, 32, v238
	v_cmp_lt_i32_e32 vcc, v75, v76
	s_nop 1
	v_cndmask_b32_e32 v75, v238, v75, vcc
	v_lshlrev_b32_e32 v75, 2, v75
	v_mov_b32_e32 v75, v74
	s_nop 1
	v_permlane32_swap_b32 v75, v74
	s_waitcnt lgkmcnt(0)
	v_add_f32_e32 v74, v74, v75
	v_fmamk_f32 v74, v74, 0x3c800000, v236
	v_rsq_f32_e32 v86, v74
	v_lshrrev_b32_e32 v74, 2, v106
	v_and_b32_e32 v74, 0x3f0, v74
	v_add_u32_e32 v74, v74, v177
	v_lshl_add_u32 v78, v74, 3, s5
	ds_read_b128 v[74:77], v78
	ds_read_b128 v[80:83], v78 offset:16
	v_pk_mul_f32 v[78:79], v[54:55], v[86:87] op_sel_hi:[1,0]
	v_pk_mul_f32 v[84:85], v[154:155], v[86:87] op_sel_hi:[1,0]
	v_pk_mul_f32 v[78:79], v[100:101], v[78:79]
	v_pk_mul_f32 v[84:85], v[102:103], v[84:85]
	s_waitcnt lgkmcnt(0)
	v_mov_b32_e32 v101, v76
	v_mov_b32_e32 v102, v74
	v_mov_b32_e32 v103, v77
	v_mov_b32_e32 v108, v76
	v_mov_b32_e32 v109, v74
	v_mov_b32_e32 v74, v77
	v_pk_mov_b32 v[76:77], v[84:85], v[78:79] op_sel:[1,0]
	v_mov_b32_e32 v100, v75
	v_pk_mul_f32 v[102:103], v[102:103], v[78:79]
	v_pk_mul_f32 v[74:75], v[74:75], v[76:77]
	v_pk_mul_f32 v[76:77], v[56:57], v[86:87] op_sel_hi:[1,0]
	v_pk_mov_b32 v[110:111], v[78:79], v[84:85] op_sel:[1,0]
	v_pk_fma_f32 v[78:79], v[100:101], v[84:85], v[102:103]
	v_pk_mul_f32 v[76:77], v[96:97], v[76:77]
	v_mov_b32_e32 v97, v82
	v_mov_b32_e32 v100, v82
	v_lshlrev_b32_e32 v82, 4, v107
	v_pk_mul_f32 v[84:85], v[152:153], v[86:87] op_sel_hi:[1,0]
	v_and_b32_e32 v82, 0x3f0, v82
	v_pk_mul_f32 v[84:85], v[98:99], v[84:85]
	v_mov_b32_e32 v98, v80
	v_mov_b32_e32 v99, v83
	v_add_u32_e32 v82, v82, v177
	v_mov_b32_e32 v96, v81
	v_pk_mul_f32 v[98:99], v[98:99], v[76:77]
	v_mov_b32_e32 v101, v80
	v_pk_mov_b32 v[102:103], v[76:77], v[84:85] op_sel:[1,0]
	v_mov_b32_e32 v80, v83
	v_pk_mov_b32 v[76:77], v[84:85], v[76:77] op_sel:[1,0]
	v_lshl_add_u32 v87, v82, 3, s5
	v_pk_mul_f32 v[76:77], v[80:81], v[76:77]
	v_pk_fma_f32 v[80:81], v[96:97], v[84:85], v[98:99]
	ds_read_b128 v[82:85], v87
	ds_read_b128 v[96:99], v87 offset:16
	v_pk_fma_f32 v[76:77], v[100:101], v[102:103], v[76:77] neg_lo:[0,0,1] neg_hi:[0,0,1]
	v_pk_mul_f32 v[100:101], v[46:47], v[86:87] op_sel_hi:[1,0]
	v_pk_fma_f32 v[74:75], v[108:109], v[110:111], v[74:75] neg_lo:[0,0,1] neg_hi:[0,0,1]
	v_pk_mul_f32 v[92:93], v[92:93], v[100:101]
	v_pk_mul_f32 v[100:101], v[150:151], v[86:87] op_sel_hi:[1,0]
	s_waitcnt lgkmcnt(0)
	v_mov_b32_e32 v102, v82
	v_pk_mul_f32 v[94:95], v[94:95], v[100:101]
	v_mov_b32_e32 v103, v85
	v_mov_b32_e32 v101, v84
	v_pk_mul_f32 v[102:103], v[102:103], v[92:93]
	v_mov_b32_e32 v108, v84
	v_mov_b32_e32 v109, v82
	v_pk_mov_b32 v[110:111], v[92:93], v[94:95] op_sel:[1,0]
	v_mov_b32_e32 v82, v85
	v_pk_mov_b32 v[84:85], v[94:95], v[92:93] op_sel:[1,0]
	v_pk_mul_f32 v[92:93], v[48:49], v[86:87] op_sel_hi:[1,0]
	v_pk_mul_f32 v[86:87], v[148:149], v[86:87] op_sel_hi:[1,0]
	v_mov_b32_e32 v100, v83
	v_pk_mul_f32 v[82:83], v[82:83], v[84:85]
	v_pk_mul_f32 v[88:89], v[88:89], v[92:93]
	v_pk_mul_f32 v[90:91], v[90:91], v[86:87]
	v_mov_b32_e32 v86, v96
	v_mov_b32_e32 v87, v99
	v_pk_fma_f32 v[84:85], v[108:109], v[110:111], v[82:83] neg_lo:[0,0,1] neg_hi:[0,0,1]
	v_pk_fma_f32 v[82:83], v[100:101], v[94:95], v[102:103]
	v_pk_mul_f32 v[94:95], v[86:87], v[88:89]
	v_mov_b32_e32 v87, v96
	v_pk_mov_b32 v[100:101], v[88:89], v[90:91] op_sel:[1,0]
	v_mov_b32_e32 v96, v99
	v_pk_mov_b32 v[88:89], v[90:91], v[88:89] op_sel:[1,0]
	v_mov_b32_e32 v92, v97
	v_mov_b32_e32 v93, v98
	v_mov_b32_e32 v86, v98
	v_pk_mul_f32 v[88:89], v[96:97], v[88:89]
	s_nop 0
	v_pk_fma_f32 v[86:87], v[86:87], v[100:101], v[88:89] neg_lo:[0,0,1] neg_hi:[0,0,1]
	v_pk_fma_f32 v[88:89], v[92:93], v[90:91], v[94:95]
	s_and_b64 vcc, exec, s[42:43]
	s_cbranch_vccz .LBB0_800
	s_branch .LBB0_801

.LBB0_805:
	v_mov_b32_e32 v89, v175
	s_nop 0
	v_mov_b32_e32 v75, v71
	v_lshl_add_u32 v74, v89, 2, s97
	ds_read_b32 v88, v74 offset:512
	v_mov_b32_e32 v71, v67
	v_mov_b32_e32 v74, v66
	s_addk_i32 s4, 0x80
	v_add_u32_e32 v90, s4, v89
	s_waitcnt lgkmcnt(0)
	v_pk_mul_f32 v[86:87], v[70:71], v[88:89] op_sel_hi:[1,0]
	v_mov_b32_e32 v70, v68
	v_mov_b32_e32 v71, v73
	v_pk_mul_f32 v[80:81], v[70:71], v[88:89] op_sel_hi:[1,0]
	v_mov_b32_e32 v71, v63
	v_mov_b32_e32 v63, v59
	v_mov_b32_e32 v73, v69
	v_pk_mul_f32 v[78:79], v[62:63], v[88:89] op_sel_hi:[1,0]
	v_mov_b32_e32 v62, v60
	v_mov_b32_e32 v63, v65
	v_mov_b32_e32 v65, v61
	v_pk_mul_f32 v[84:85], v[74:75], v[88:89] op_sel_hi:[1,0]
	v_pk_mul_f32 v[82:83], v[72:73], v[88:89] op_sel_hi:[1,0]
	v_mov_b32_e32 v70, v58
	v_pk_mul_f32 v[72:73], v[62:63], v[88:89] op_sel_hi:[1,0]
	v_pk_mul_f32 v[74:75], v[64:65], v[88:89] op_sel_hi:[1,0]
	v_pk_mul_f32 v[76:77], v[70:71], v[88:89] op_sel_hi:[1,0]
	s_and_b64 vcc, exec, s[40:41]
	v_pk_mov_b32 v[70:71], v[72:73], v[74:75] op_sel:[1,0]
	s_cbranch_vccnz .LBB0_807
	v_pk_mul_f32 v[58:59], v[86:87], v[86:87]
	v_pk_mul_f32 v[60:61], v[84:85], v[84:85]
	v_pk_mul_f32 v[62:63], v[82:83], v[82:83]
	v_add_f32_e32 v58, v58, v61
	v_pk_mul_f32 v[64:65], v[80:81], v[80:81]
	v_add_f32_e32 v58, v62, v58
	v_add_f32_e32 v58, v65, v58
	v_add_f32_e32 v58, v60, v58
	v_add_f32_e32 v58, v59, v58
	v_add_f32_e32 v58, v64, v58
	v_add_f32_e32 v58, v63, v58
	v_fmac_f32_e32 v58, v78, v78
	v_pk_mul_f32 v[66:67], v[70:71], v[70:71]
	v_fmac_f32_e32 v58, v77, v77
	v_pk_mov_b32 v[68:69], v[78:79], v[76:77] op_sel:[1,0]
	v_add_f32_e32 v58, v67, v58
	v_pk_mul_f32 v[68:69], v[68:69], v[68:69]
	v_add_f32_e32 v58, v66, v58
	v_and_b32_e32 v60, 64, v238
	v_pk_mov_b32 v[70:71], v[74:75], v[72:73] op_sel:[1,0]
	v_add_f32_e32 v58, v69, v58
	v_xor_b32_e32 v59, 16, v238
	v_add_u32_e32 v60, 64, v60
	v_pk_mul_f32 v[70:71], v[70:71], v[70:71]
	v_add_f32_e32 v58, v68, v58
	v_cmp_lt_i32_e32 vcc, v59, v60
	v_add_f32_e32 v58, v71, v58
	v_add_f32_e32 v58, v70, v58
	v_cndmask_b32_e32 v59, v238, v59, vcc
	v_lshlrev_b32_e32 v59, 2, v59
	v_mov_b32_e32 v59, v58
	s_nop 1
	v_permlane16_swap_b32 v59, v58
	v_readlane_b32 s4, v253, 18
	s_waitcnt lgkmcnt(0)
	v_add_f32_e32 v58, v58, v59
	v_xor_b32_e32 v59, 32, v238
	v_cmp_lt_i32_e32 vcc, v59, v60
	s_nop 1
	v_cndmask_b32_e32 v59, v238, v59, vcc
	v_lshlrev_b32_e32 v59, 2, v59
	v_mov_b32_e32 v59, v58
	s_nop 1
	v_permlane32_swap_b32 v59, v58
	s_waitcnt lgkmcnt(0)
	v_add_f32_e32 v58, v58, v59
	v_fmamk_f32 v58, v58, 0x3c800000, v236
	v_rsq_f32_e32 v70, v58
	v_lshrrev_b32_e32 v58, 2, v90
	v_and_b32_e32 v58, 0x3f0, v58
	v_add_u32_e32 v58, v58, v177
	v_lshl_add_u32 v62, v58, 3, s4
	ds_read_b128 v[58:61], v62
	ds_read_b128 v[64:67], v62 offset:16
	v_pk_mul_f32 v[62:63], v[54:55], v[70:71] op_sel_hi:[1,0]
	v_pk_mul_f32 v[68:69], v[154:155], v[70:71] op_sel_hi:[1,0]
	v_pk_mul_f32 v[62:63], v[84:85], v[62:63]
	v_pk_mul_f32 v[68:69], v[86:87], v[68:69]
	s_waitcnt lgkmcnt(0)
	v_mov_b32_e32 v85, v60
	v_mov_b32_e32 v86, v58
	v_mov_b32_e32 v87, v61
	v_mov_b32_e32 v92, v60
	v_mov_b32_e32 v93, v58
	v_mov_b32_e32 v58, v61
	v_pk_mov_b32 v[60:61], v[68:69], v[62:63] op_sel:[1,0]
	v_mov_b32_e32 v84, v59
	v_pk_mul_f32 v[86:87], v[86:87], v[62:63]
	v_pk_mul_f32 v[58:59], v[58:59], v[60:61]
	v_pk_mul_f32 v[60:61], v[56:57], v[70:71] op_sel_hi:[1,0]
	v_pk_mov_b32 v[94:95], v[62:63], v[68:69] op_sel:[1,0]
	v_pk_fma_f32 v[62:63], v[84:85], v[68:69], v[86:87]
	v_pk_mul_f32 v[60:61], v[80:81], v[60:61]
	v_mov_b32_e32 v81, v66
	v_mov_b32_e32 v84, v66
	v_lshlrev_b32_e32 v66, 4, v89
	v_pk_mul_f32 v[68:69], v[152:153], v[70:71] op_sel_hi:[1,0]
	v_and_b32_e32 v66, 0x3f0, v66
	v_pk_mul_f32 v[68:69], v[82:83], v[68:69]
	v_mov_b32_e32 v82, v64
	v_mov_b32_e32 v83, v67
	v_add_u32_e32 v66, v66, v177
	v_mov_b32_e32 v80, v65
	v_pk_mul_f32 v[82:83], v[82:83], v[60:61]
	v_mov_b32_e32 v85, v64
	v_pk_mov_b32 v[86:87], v[60:61], v[68:69] op_sel:[1,0]
	v_mov_b32_e32 v64, v67
	v_pk_mov_b32 v[60:61], v[68:69], v[60:61] op_sel:[1,0]
	v_lshl_add_u32 v71, v66, 3, s4
	v_pk_mul_f32 v[60:61], v[64:65], v[60:61]
	v_pk_fma_f32 v[64:65], v[80:81], v[68:69], v[82:83]
	ds_read_b128 v[66:69], v71
	ds_read_b128 v[80:83], v71 offset:16
	v_pk_fma_f32 v[60:61], v[84:85], v[86:87], v[60:61] neg_lo:[0,0,1] neg_hi:[0,0,1]
	v_pk_mul_f32 v[84:85], v[46:47], v[70:71] op_sel_hi:[1,0]
	v_pk_fma_f32 v[58:59], v[92:93], v[94:95], v[58:59] neg_lo:[0,0,1] neg_hi:[0,0,1]
	v_pk_mul_f32 v[76:77], v[76:77], v[84:85]
	v_pk_mul_f32 v[84:85], v[150:151], v[70:71] op_sel_hi:[1,0]
	s_waitcnt lgkmcnt(0)
	v_mov_b32_e32 v86, v66
	v_pk_mul_f32 v[78:79], v[78:79], v[84:85]
	v_mov_b32_e32 v87, v69
	v_mov_b32_e32 v85, v68
	v_pk_mul_f32 v[86:87], v[86:87], v[76:77]
	v_mov_b32_e32 v92, v68
	v_mov_b32_e32 v93, v66
	v_pk_mov_b32 v[94:95], v[76:77], v[78:79] op_sel:[1,0]
	v_mov_b32_e32 v66, v69
	v_pk_mov_b32 v[68:69], v[78:79], v[76:77] op_sel:[1,0]
	v_pk_mul_f32 v[76:77], v[48:49], v[70:71] op_sel_hi:[1,0]
	v_pk_mul_f32 v[70:71], v[148:149], v[70:71] op_sel_hi:[1,0]
	v_mov_b32_e32 v84, v67
	v_pk_mul_f32 v[66:67], v[66:67], v[68:69]
	v_pk_mul_f32 v[72:73], v[72:73], v[76:77]
	v_pk_mul_f32 v[74:75], v[74:75], v[70:71]
	v_mov_b32_e32 v70, v80
	v_mov_b32_e32 v71, v83
	v_pk_fma_f32 v[68:69], v[92:93], v[94:95], v[66:67] neg_lo:[0,0,1] neg_hi:[0,0,1]
	v_pk_fma_f32 v[66:67], v[84:85], v[78:79], v[86:87]
	v_pk_mul_f32 v[78:79], v[70:71], v[72:73]
	v_mov_b32_e32 v71, v80
	v_pk_mov_b32 v[84:85], v[72:73], v[74:75] op_sel:[1,0]
	v_mov_b32_e32 v80, v83
	v_pk_mov_b32 v[72:73], v[74:75], v[72:73] op_sel:[1,0]
	v_mov_b32_e32 v76, v81
	v_mov_b32_e32 v77, v82
	v_mov_b32_e32 v70, v82
	v_pk_mul_f32 v[72:73], v[80:81], v[72:73]
	s_nop 0
	v_pk_fma_f32 v[70:71], v[70:71], v[84:85], v[72:73] neg_lo:[0,0,1] neg_hi:[0,0,1]
	v_pk_fma_f32 v[72:73], v[76:77], v[74:75], v[78:79]
	s_and_b64 vcc, exec, s[42:43]
	s_cbranch_vccz .LBB0_808
	s_branch .LBB0_809

.LBB0_813:
	v_mov_b32_e32 v73, v175
	s_nop 0
	v_mov_b32_e32 v59, v51
	v_lshl_add_u32 v58, v73, 2, s97
	ds_read_b32 v72, v58 offset:576
	v_mov_b32_e32 v51, v43
	s_add_i32 s4, s94, 0x90
	v_mov_b32_e32 v58, v42
	v_add_u32_e32 v75, s4, v73
	s_waitcnt lgkmcnt(0)
	v_pk_mul_f32 v[70:71], v[50:51], v[72:73] op_sel_hi:[1,0]
	v_mov_b32_e32 v50, v44
	v_mov_b32_e32 v51, v53
	v_pk_mul_f32 v[64:65], v[50:51], v[72:73] op_sel_hi:[1,0]
	v_mov_b32_e32 v51, v39
	v_mov_b32_e32 v39, v35
	v_mov_b32_e32 v53, v45
	v_pk_mul_f32 v[62:63], v[38:39], v[72:73] op_sel_hi:[1,0]
	v_mov_b32_e32 v38, v36
	v_mov_b32_e32 v39, v41
	v_mov_b32_e32 v41, v37
	v_pk_mul_f32 v[68:69], v[58:59], v[72:73] op_sel_hi:[1,0]
	v_pk_mul_f32 v[66:67], v[52:53], v[72:73] op_sel_hi:[1,0]
	v_mov_b32_e32 v50, v34
	v_pk_mul_f32 v[52:53], v[38:39], v[72:73] op_sel_hi:[1,0]
	v_pk_mul_f32 v[58:59], v[40:41], v[72:73] op_sel_hi:[1,0]
	v_add_u32_e32 v74, s66, v75
	v_pk_mul_f32 v[60:61], v[50:51], v[72:73] op_sel_hi:[1,0]
	s_and_b64 vcc, exec, s[40:41]
	v_pk_mov_b32 v[50:51], v[52:53], v[58:59] op_sel:[1,0]
	s_cbranch_vccnz .LBB0_815
	v_pk_mul_f32 v[34:35], v[70:71], v[70:71]
	v_pk_mul_f32 v[36:37], v[68:69], v[68:69]
	v_pk_mul_f32 v[38:39], v[66:67], v[66:67]
	v_add_f32_e32 v34, v34, v37
	v_pk_mul_f32 v[40:41], v[64:65], v[64:65]
	v_add_f32_e32 v34, v38, v34
	v_add_f32_e32 v34, v41, v34
	v_add_f32_e32 v34, v36, v34
	v_add_f32_e32 v34, v35, v34
	v_add_f32_e32 v34, v40, v34
	v_add_f32_e32 v34, v39, v34
	v_fmac_f32_e32 v34, v62, v62
	v_pk_mul_f32 v[42:43], v[50:51], v[50:51]
	v_fmac_f32_e32 v34, v61, v61
	v_pk_mov_b32 v[44:45], v[62:63], v[60:61] op_sel:[1,0]
	v_add_f32_e32 v34, v43, v34
	v_pk_mul_f32 v[44:45], v[44:45], v[44:45]
	v_add_f32_e32 v34, v42, v34
	v_and_b32_e32 v36, 64, v238
	v_pk_mov_b32 v[50:51], v[58:59], v[52:53] op_sel:[1,0]
	v_add_f32_e32 v34, v45, v34
	v_xor_b32_e32 v35, 16, v238
	v_add_u32_e32 v36, 64, v36
	v_pk_mul_f32 v[50:51], v[50:51], v[50:51]
	v_add_f32_e32 v34, v44, v34
	v_cmp_lt_i32_e32 vcc, v35, v36
	v_add_f32_e32 v34, v51, v34
	v_add_f32_e32 v34, v50, v34
	v_cndmask_b32_e32 v35, v238, v35, vcc
	v_lshlrev_b32_e32 v35, 2, v35
	v_mov_b32_e32 v35, v34
	s_nop 1
	v_permlane16_swap_b32 v35, v34
	v_readlane_b32 s4, v253, 18
	s_waitcnt lgkmcnt(0)
	v_add_f32_e32 v34, v34, v35
	v_xor_b32_e32 v35, 32, v238
	v_cmp_lt_i32_e32 vcc, v35, v36
	s_nop 1
	v_cndmask_b32_e32 v35, v238, v35, vcc
	v_lshlrev_b32_e32 v35, 2, v35
	v_mov_b32_e32 v35, v34
	s_nop 1
	v_permlane32_swap_b32 v35, v34
	s_waitcnt lgkmcnt(0)
	v_add_f32_e32 v34, v34, v35
	v_fmamk_f32 v34, v34, 0x3c800000, v236
	v_rsq_f32_e32 v50, v34
	v_lshrrev_b32_e32 v34, 2, v74
	v_and_b32_e32 v34, 0x3f0, v34
	v_add_u32_e32 v34, v34, v177
	v_lshl_add_u32 v38, v34, 3, s4
	ds_read_b128 v[34:37], v38
	ds_read_b128 v[40:43], v38 offset:16
	v_pk_mul_f32 v[38:39], v[54:55], v[50:51] op_sel_hi:[1,0]
	v_pk_mul_f32 v[44:45], v[154:155], v[50:51] op_sel_hi:[1,0]
	v_pk_mul_f32 v[38:39], v[68:69], v[38:39]
	v_pk_mul_f32 v[44:45], v[70:71], v[44:45]
	s_waitcnt lgkmcnt(0)
	v_mov_b32_e32 v69, v36
	v_mov_b32_e32 v70, v34
	v_mov_b32_e32 v71, v37
	v_mov_b32_e32 v76, v36
	v_mov_b32_e32 v77, v34
	v_mov_b32_e32 v34, v37
	v_pk_mov_b32 v[36:37], v[44:45], v[38:39] op_sel:[1,0]
	v_mov_b32_e32 v68, v35
	v_pk_mul_f32 v[70:71], v[70:71], v[38:39]
	v_pk_mul_f32 v[34:35], v[34:35], v[36:37]
	v_pk_mul_f32 v[36:37], v[56:57], v[50:51] op_sel_hi:[1,0]
	v_pk_mov_b32 v[78:79], v[38:39], v[44:45] op_sel:[1,0]
	v_pk_fma_f32 v[38:39], v[68:69], v[44:45], v[70:71]
	v_pk_mul_f32 v[36:37], v[64:65], v[36:37]
	v_mov_b32_e32 v65, v42
	v_mov_b32_e32 v68, v42
	v_lshlrev_b32_e32 v42, 4, v75
	v_pk_mul_f32 v[44:45], v[152:153], v[50:51] op_sel_hi:[1,0]
	v_and_b32_e32 v42, 0x3f0, v42
	v_pk_mul_f32 v[44:45], v[66:67], v[44:45]
	v_mov_b32_e32 v66, v40
	v_mov_b32_e32 v67, v43
	v_add_u32_e32 v42, v42, v177
	v_mov_b32_e32 v64, v41
	v_pk_mul_f32 v[66:67], v[66:67], v[36:37]
	v_mov_b32_e32 v69, v40
	v_pk_mov_b32 v[70:71], v[36:37], v[44:45] op_sel:[1,0]
	v_mov_b32_e32 v40, v43
	v_pk_mov_b32 v[36:37], v[44:45], v[36:37] op_sel:[1,0]
	v_lshl_add_u32 v51, v42, 3, s4
	v_pk_mul_f32 v[36:37], v[40:41], v[36:37]
	v_pk_fma_f32 v[40:41], v[64:65], v[44:45], v[66:67]
	ds_read_b128 v[42:45], v51
	ds_read_b128 v[64:67], v51 offset:16
	v_pk_fma_f32 v[36:37], v[68:69], v[70:71], v[36:37] neg_lo:[0,0,1] neg_hi:[0,0,1]
	v_pk_mul_f32 v[68:69], v[46:47], v[50:51] op_sel_hi:[1,0]
	v_pk_fma_f32 v[34:35], v[76:77], v[78:79], v[34:35] neg_lo:[0,0,1] neg_hi:[0,0,1]
	v_pk_mul_f32 v[60:61], v[60:61], v[68:69]
	v_pk_mul_f32 v[68:69], v[150:151], v[50:51] op_sel_hi:[1,0]
	s_waitcnt lgkmcnt(0)
	v_mov_b32_e32 v70, v42
	v_pk_mul_f32 v[62:63], v[62:63], v[68:69]
	v_mov_b32_e32 v71, v45
	v_mov_b32_e32 v69, v44
	v_pk_mul_f32 v[70:71], v[70:71], v[60:61]
	v_mov_b32_e32 v76, v44
	v_mov_b32_e32 v77, v42
	v_pk_mov_b32 v[78:79], v[60:61], v[62:63] op_sel:[1,0]
	v_mov_b32_e32 v42, v45
	v_pk_mov_b32 v[44:45], v[62:63], v[60:61] op_sel:[1,0]
	v_pk_mul_f32 v[60:61], v[48:49], v[50:51] op_sel_hi:[1,0]
	v_pk_mul_f32 v[50:51], v[148:149], v[50:51] op_sel_hi:[1,0]
	v_mov_b32_e32 v68, v43
	v_pk_mul_f32 v[42:43], v[42:43], v[44:45]
	v_pk_mul_f32 v[52:53], v[52:53], v[60:61]
	v_pk_mul_f32 v[58:59], v[58:59], v[50:51]
	v_mov_b32_e32 v50, v64
	v_mov_b32_e32 v51, v67
	v_pk_fma_f32 v[44:45], v[76:77], v[78:79], v[42:43] neg_lo:[0,0,1] neg_hi:[0,0,1]
	v_pk_fma_f32 v[42:43], v[68:69], v[62:63], v[70:71]
	v_pk_mul_f32 v[62:63], v[50:51], v[52:53]
	v_mov_b32_e32 v51, v64
	v_pk_mov_b32 v[68:69], v[52:53], v[58:59] op_sel:[1,0]
	v_mov_b32_e32 v64, v67
	v_pk_mov_b32 v[52:53], v[58:59], v[52:53] op_sel:[1,0]
	v_mov_b32_e32 v60, v65
	v_mov_b32_e32 v61, v66
	v_mov_b32_e32 v50, v66
	v_pk_mul_f32 v[52:53], v[64:65], v[52:53]
	s_nop 0
	v_pk_fma_f32 v[50:51], v[50:51], v[68:69], v[52:53] neg_lo:[0,0,1] neg_hi:[0,0,1]
	v_pk_fma_f32 v[52:53], v[60:61], v[58:59], v[62:63]
	s_and_b64 vcc, exec, s[42:43]
	s_cbranch_vccz .LBB0_816
	s_branch .LBB0_817

.LBB0_821:
	v_mov_b32_e32 v53, v175
	s_nop 0
	v_mov_b32_e32 v35, v29
	v_lshl_add_u32 v34, v53, 2, s97
	ds_read_b32 v52, v34 offset:640
	v_mov_b32_e32 v29, v25
	s_add_i32 s4, s94, 0xa0
	v_mov_b32_e32 v34, v24
	v_add_u32_e32 v59, s4, v53
	s_waitcnt lgkmcnt(0)
	v_pk_mul_f32 v[50:51], v[28:29], v[52:53] op_sel_hi:[1,0]
	v_mov_b32_e32 v28, v26
	v_mov_b32_e32 v29, v31
	v_pk_mul_f32 v[40:41], v[28:29], v[52:53] op_sel_hi:[1,0]
	v_mov_b32_e32 v29, v21
	v_mov_b32_e32 v21, v17
	v_mov_b32_e32 v31, v27
	v_pk_mul_f32 v[38:39], v[20:21], v[52:53] op_sel_hi:[1,0]
	v_mov_b32_e32 v20, v18
	v_mov_b32_e32 v21, v23
	v_mov_b32_e32 v23, v19
	v_pk_mul_f32 v[44:45], v[34:35], v[52:53] op_sel_hi:[1,0]
	v_pk_mul_f32 v[42:43], v[30:31], v[52:53] op_sel_hi:[1,0]
	v_mov_b32_e32 v28, v16
	v_pk_mul_f32 v[30:31], v[20:21], v[52:53] op_sel_hi:[1,0]
	v_pk_mul_f32 v[34:35], v[22:23], v[52:53] op_sel_hi:[1,0]
	v_add_u32_e32 v58, s66, v59
	v_pk_mul_f32 v[36:37], v[28:29], v[52:53] op_sel_hi:[1,0]
	s_and_b64 vcc, exec, s[40:41]
	v_pk_mov_b32 v[28:29], v[30:31], v[34:35] op_sel:[1,0]
	s_cbranch_vccnz .LBB0_823
	v_pk_mul_f32 v[16:17], v[50:51], v[50:51]
	v_pk_mul_f32 v[18:19], v[44:45], v[44:45]
	v_pk_mul_f32 v[20:21], v[42:43], v[42:43]
	v_add_f32_e32 v16, v16, v19
	v_pk_mul_f32 v[22:23], v[40:41], v[40:41]
	v_add_f32_e32 v16, v20, v16
	v_add_f32_e32 v16, v23, v16
	v_add_f32_e32 v16, v18, v16
	v_add_f32_e32 v16, v17, v16
	v_add_f32_e32 v16, v22, v16
	v_add_f32_e32 v16, v21, v16
	v_fmac_f32_e32 v16, v38, v38
	v_pk_mul_f32 v[24:25], v[28:29], v[28:29]
	v_fmac_f32_e32 v16, v37, v37
	v_pk_mov_b32 v[26:27], v[38:39], v[36:37] op_sel:[1,0]
	v_add_f32_e32 v16, v25, v16
	v_pk_mul_f32 v[26:27], v[26:27], v[26:27]
	v_add_f32_e32 v16, v24, v16
	v_and_b32_e32 v18, 64, v238
	v_pk_mov_b32 v[28:29], v[34:35], v[30:31] op_sel:[1,0]
	v_add_f32_e32 v16, v27, v16
	v_xor_b32_e32 v17, 16, v238
	v_add_u32_e32 v18, 64, v18
	v_pk_mul_f32 v[28:29], v[28:29], v[28:29]
	v_add_f32_e32 v16, v26, v16
	v_cmp_lt_i32_e32 vcc, v17, v18
	v_add_f32_e32 v16, v29, v16
	v_add_f32_e32 v16, v28, v16
	v_cndmask_b32_e32 v17, v238, v17, vcc
	v_lshlrev_b32_e32 v17, 2, v17
	v_mov_b32_e32 v17, v16
	s_nop 1
	v_permlane16_swap_b32 v17, v16
	v_readlane_b32 s4, v253, 18
	s_waitcnt lgkmcnt(0)
	v_add_f32_e32 v16, v16, v17
	v_xor_b32_e32 v17, 32, v238
	v_cmp_lt_i32_e32 vcc, v17, v18
	s_nop 1
	v_cndmask_b32_e32 v17, v238, v17, vcc
	v_lshlrev_b32_e32 v17, 2, v17
	v_mov_b32_e32 v17, v16
	s_nop 1
	v_permlane32_swap_b32 v17, v16
	s_waitcnt lgkmcnt(0)
	v_add_f32_e32 v16, v16, v17
	v_fmamk_f32 v16, v16, 0x3c800000, v236
	v_rsq_f32_e32 v28, v16
	v_lshrrev_b32_e32 v16, 2, v58
	v_and_b32_e32 v16, 0x3f0, v16
	v_add_u32_e32 v16, v16, v177
	v_lshl_add_u32 v20, v16, 3, s4
	ds_read_b128 v[16:19], v20
	ds_read_b128 v[22:25], v20 offset:16
	v_pk_mul_f32 v[20:21], v[54:55], v[28:29] op_sel_hi:[1,0]
	v_pk_mul_f32 v[26:27], v[154:155], v[28:29] op_sel_hi:[1,0]
	v_pk_mul_f32 v[20:21], v[44:45], v[20:21]
	v_pk_mul_f32 v[26:27], v[50:51], v[26:27]
	s_waitcnt lgkmcnt(0)
	v_mov_b32_e32 v45, v18
	v_mov_b32_e32 v50, v16
	v_mov_b32_e32 v51, v19
	v_mov_b32_e32 v60, v18
	v_mov_b32_e32 v61, v16
	v_mov_b32_e32 v16, v19
	v_pk_mov_b32 v[18:19], v[26:27], v[20:21] op_sel:[1,0]
	v_mov_b32_e32 v44, v17
	v_pk_mul_f32 v[50:51], v[50:51], v[20:21]
	v_pk_mul_f32 v[16:17], v[16:17], v[18:19]
	v_pk_mul_f32 v[18:19], v[56:57], v[28:29] op_sel_hi:[1,0]
	v_pk_mov_b32 v[62:63], v[20:21], v[26:27] op_sel:[1,0]
	v_pk_fma_f32 v[20:21], v[44:45], v[26:27], v[50:51]
	v_pk_mul_f32 v[18:19], v[40:41], v[18:19]
	v_mov_b32_e32 v41, v24
	v_mov_b32_e32 v44, v24
	v_lshlrev_b32_e32 v24, 4, v59
	v_pk_mul_f32 v[26:27], v[152:153], v[28:29] op_sel_hi:[1,0]
	v_and_b32_e32 v24, 0x3f0, v24
	v_pk_mul_f32 v[26:27], v[42:43], v[26:27]
	v_mov_b32_e32 v42, v22
	v_mov_b32_e32 v43, v25
	v_add_u32_e32 v24, v24, v177
	v_mov_b32_e32 v40, v23
	v_pk_mul_f32 v[42:43], v[42:43], v[18:19]
	v_mov_b32_e32 v45, v22
	v_pk_mov_b32 v[50:51], v[18:19], v[26:27] op_sel:[1,0]
	v_mov_b32_e32 v22, v25
	v_pk_mov_b32 v[18:19], v[26:27], v[18:19] op_sel:[1,0]
	v_lshl_add_u32 v29, v24, 3, s4
	v_pk_mul_f32 v[18:19], v[22:23], v[18:19]
	v_pk_fma_f32 v[22:23], v[40:41], v[26:27], v[42:43]
	ds_read_b128 v[24:27], v29
	ds_read_b128 v[40:43], v29 offset:16
	v_pk_fma_f32 v[18:19], v[44:45], v[50:51], v[18:19] neg_lo:[0,0,1] neg_hi:[0,0,1]
	v_pk_mul_f32 v[44:45], v[46:47], v[28:29] op_sel_hi:[1,0]
	v_pk_fma_f32 v[16:17], v[60:61], v[62:63], v[16:17] neg_lo:[0,0,1] neg_hi:[0,0,1]
	v_pk_mul_f32 v[36:37], v[36:37], v[44:45]
	v_pk_mul_f32 v[44:45], v[150:151], v[28:29] op_sel_hi:[1,0]
	s_waitcnt lgkmcnt(0)
	v_mov_b32_e32 v50, v24
	v_pk_mul_f32 v[38:39], v[38:39], v[44:45]
	v_mov_b32_e32 v51, v27
	v_mov_b32_e32 v45, v26
	v_pk_mul_f32 v[50:51], v[50:51], v[36:37]
	v_mov_b32_e32 v60, v26
	v_mov_b32_e32 v61, v24
	v_pk_mov_b32 v[62:63], v[36:37], v[38:39] op_sel:[1,0]
	v_mov_b32_e32 v24, v27
	v_pk_mov_b32 v[26:27], v[38:39], v[36:37] op_sel:[1,0]
	v_pk_mul_f32 v[36:37], v[48:49], v[28:29] op_sel_hi:[1,0]
	v_pk_mul_f32 v[28:29], v[148:149], v[28:29] op_sel_hi:[1,0]
	v_mov_b32_e32 v44, v25
	v_pk_mul_f32 v[24:25], v[24:25], v[26:27]
	v_pk_mul_f32 v[30:31], v[30:31], v[36:37]
	v_pk_mul_f32 v[34:35], v[34:35], v[28:29]
	v_mov_b32_e32 v28, v40
	v_mov_b32_e32 v29, v43
	v_pk_fma_f32 v[26:27], v[60:61], v[62:63], v[24:25] neg_lo:[0,0,1] neg_hi:[0,0,1]
	v_pk_fma_f32 v[24:25], v[44:45], v[38:39], v[50:51]
	v_pk_mul_f32 v[38:39], v[28:29], v[30:31]
	v_mov_b32_e32 v29, v40
	v_pk_mov_b32 v[44:45], v[30:31], v[34:35] op_sel:[1,0]
	v_mov_b32_e32 v40, v43
	v_pk_mov_b32 v[30:31], v[34:35], v[30:31] op_sel:[1,0]
	v_mov_b32_e32 v36, v41
	v_mov_b32_e32 v37, v42
	v_mov_b32_e32 v28, v42
	v_pk_mul_f32 v[30:31], v[40:41], v[30:31]
	s_nop 0
	v_pk_fma_f32 v[28:29], v[28:29], v[44:45], v[30:31] neg_lo:[0,0,1] neg_hi:[0,0,1]
	v_pk_fma_f32 v[30:31], v[36:37], v[34:35], v[38:39]
	s_and_b64 vcc, exec, s[42:43]
	s_cbranch_vccz .LBB0_824
	s_branch .LBB0_825

.LBB0_829:
	s_addk_i32 s94, 0xb0
	s_nop 0
	v_lshl_add_u32 v16, v175, 2, s97
	ds_read_b32 v30, v16 offset:704
	v_add_u32_e32 v34, s94, v175
	v_add_u32_e32 v31, s66, v34
	v_mov_b32_e32 v17, v13
	v_mov_b32_e32 v13, v9
	s_waitcnt lgkmcnt(0)
	v_pk_mul_f32 v[28:29], v[12:13], v[30:31] op_sel_hi:[1,0]
	v_mov_b32_e32 v12, v10
	v_mov_b32_e32 v13, v15
	v_pk_mul_f32 v[22:23], v[12:13], v[30:31] op_sel_hi:[1,0]
	v_mov_b32_e32 v13, v5
	v_mov_b32_e32 v5, v1
	v_mov_b32_e32 v16, v8
	v_mov_b32_e32 v15, v11
	v_pk_mul_f32 v[20:21], v[4:5], v[30:31] op_sel_hi:[1,0]
	v_mov_b32_e32 v4, v2
	v_mov_b32_e32 v5, v7
	v_mov_b32_e32 v7, v3
	v_pk_mul_f32 v[26:27], v[16:17], v[30:31] op_sel_hi:[1,0]
	v_pk_mul_f32 v[24:25], v[14:15], v[30:31] op_sel_hi:[1,0]
	v_mov_b32_e32 v12, v0
	v_pk_mul_f32 v[14:15], v[4:5], v[30:31] op_sel_hi:[1,0]
	v_pk_mul_f32 v[16:17], v[6:7], v[30:31] op_sel_hi:[1,0]
	v_pk_mul_f32 v[18:19], v[12:13], v[30:31] op_sel_hi:[1,0]
	s_and_b64 vcc, exec, s[40:41]
	v_pk_mov_b32 v[12:13], v[14:15], v[16:17] op_sel:[1,0]
	s_cbranch_vccnz .LBB0_831
	v_pk_mul_f32 v[0:1], v[28:29], v[28:29]
	v_pk_mul_f32 v[2:3], v[26:27], v[26:27]
	v_pk_mul_f32 v[4:5], v[24:25], v[24:25]
	v_add_f32_e32 v0, v0, v3
	v_pk_mul_f32 v[6:7], v[22:23], v[22:23]
	v_add_f32_e32 v0, v4, v0
	v_add_f32_e32 v0, v7, v0
	v_add_f32_e32 v0, v2, v0
	v_add_f32_e32 v0, v1, v0
	v_add_f32_e32 v0, v6, v0
	v_add_f32_e32 v0, v5, v0
	v_fmac_f32_e32 v0, v20, v20
	v_pk_mul_f32 v[8:9], v[12:13], v[12:13]
	v_fmac_f32_e32 v0, v19, v19
	v_pk_mov_b32 v[10:11], v[20:21], v[18:19] op_sel:[1,0]
	v_add_f32_e32 v0, v9, v0
	v_pk_mul_f32 v[10:11], v[10:11], v[10:11]
	v_add_f32_e32 v0, v8, v0
	v_and_b32_e32 v2, 64, v238
	v_pk_mov_b32 v[12:13], v[16:17], v[14:15] op_sel:[1,0]
	v_add_f32_e32 v0, v11, v0
	v_xor_b32_e32 v1, 16, v238
	v_add_u32_e32 v2, 64, v2
	v_pk_mul_f32 v[12:13], v[12:13], v[12:13]
	v_add_f32_e32 v0, v10, v0
	v_cmp_lt_i32_e32 vcc, v1, v2
	v_add_f32_e32 v0, v13, v0
	v_add_f32_e32 v0, v12, v0
	v_cndmask_b32_e32 v1, v238, v1, vcc
	v_lshlrev_b32_e32 v1, 2, v1
	v_mov_b32_e32 v1, v0
	s_nop 1
	v_permlane16_swap_b32 v1, v0
	v_readlane_b32 s4, v253, 18
	s_waitcnt lgkmcnt(0)
	v_add_f32_e32 v0, v0, v1
	v_xor_b32_e32 v1, 32, v238
	v_cmp_lt_i32_e32 vcc, v1, v2
	s_nop 1
	v_cndmask_b32_e32 v1, v238, v1, vcc
	v_lshlrev_b32_e32 v1, 2, v1
	v_mov_b32_e32 v1, v0
	s_nop 1
	v_permlane32_swap_b32 v1, v0
	s_waitcnt lgkmcnt(0)
	v_add_f32_e32 v0, v0, v1
	v_fmamk_f32 v0, v0, 0x3c800000, v236
	v_rsq_f32_e32 v12, v0
	v_lshrrev_b32_e32 v0, 2, v31
	v_and_b32_e32 v0, 0x3f0, v0
	v_add_u32_e32 v0, v0, v177
	v_lshl_add_u32 v4, v0, 3, s4
	ds_read_b128 v[0:3], v4
	ds_read_b128 v[6:9], v4 offset:16
	v_pk_mul_f32 v[4:5], v[54:55], v[12:13] op_sel_hi:[1,0]
	v_pk_mul_f32 v[10:11], v[154:155], v[12:13] op_sel_hi:[1,0]
	v_pk_mul_f32 v[4:5], v[26:27], v[4:5]
	v_pk_mul_f32 v[10:11], v[28:29], v[10:11]
	s_waitcnt lgkmcnt(0)
	v_mov_b32_e32 v27, v2
	v_mov_b32_e32 v28, v0
	v_mov_b32_e32 v29, v3
	v_mov_b32_e32 v36, v2
	v_mov_b32_e32 v37, v0
	v_mov_b32_e32 v0, v3
	v_pk_mov_b32 v[2:3], v[10:11], v[4:5] op_sel:[1,0]
	v_mov_b32_e32 v26, v1
	v_pk_mul_f32 v[28:29], v[28:29], v[4:5]
	v_pk_mul_f32 v[0:1], v[0:1], v[2:3]
	v_pk_mul_f32 v[2:3], v[56:57], v[12:13] op_sel_hi:[1,0]
	v_pk_mov_b32 v[38:39], v[4:5], v[10:11] op_sel:[1,0]
	v_pk_fma_f32 v[4:5], v[26:27], v[10:11], v[28:29]
	v_pk_mul_f32 v[2:3], v[22:23], v[2:3]
	v_mov_b32_e32 v23, v8
	v_mov_b32_e32 v26, v8
	v_lshlrev_b32_e32 v8, 4, v34
	v_pk_mul_f32 v[10:11], v[152:153], v[12:13] op_sel_hi:[1,0]
	v_and_b32_e32 v8, 0x3f0, v8
	v_pk_mul_f32 v[10:11], v[24:25], v[10:11]
	v_mov_b32_e32 v24, v6
	v_mov_b32_e32 v25, v9
	v_add_u32_e32 v8, v8, v177
	v_mov_b32_e32 v22, v7
	v_pk_mul_f32 v[24:25], v[24:25], v[2:3]
	v_mov_b32_e32 v27, v6
	v_pk_mov_b32 v[28:29], v[2:3], v[10:11] op_sel:[1,0]
	v_mov_b32_e32 v6, v9
	v_pk_mov_b32 v[2:3], v[10:11], v[2:3] op_sel:[1,0]
	v_lshl_add_u32 v13, v8, 3, s4
	v_pk_mul_f32 v[2:3], v[6:7], v[2:3]
	v_pk_fma_f32 v[6:7], v[22:23], v[10:11], v[24:25]
	ds_read_b128 v[8:11], v13
	ds_read_b128 v[22:25], v13 offset:16
	v_pk_fma_f32 v[2:3], v[26:27], v[28:29], v[2:3] neg_lo:[0,0,1] neg_hi:[0,0,1]
	v_pk_mul_f32 v[26:27], v[46:47], v[12:13] op_sel_hi:[1,0]
	v_pk_fma_f32 v[0:1], v[36:37], v[38:39], v[0:1] neg_lo:[0,0,1] neg_hi:[0,0,1]
	v_pk_mul_f32 v[18:19], v[18:19], v[26:27]
	v_pk_mul_f32 v[26:27], v[150:151], v[12:13] op_sel_hi:[1,0]
	s_waitcnt lgkmcnt(0)
	v_mov_b32_e32 v28, v8
	v_pk_mul_f32 v[20:21], v[20:21], v[26:27]
	v_mov_b32_e32 v29, v11
	v_mov_b32_e32 v27, v10
	v_pk_mul_f32 v[28:29], v[28:29], v[18:19]
	v_mov_b32_e32 v34, v10
	v_mov_b32_e32 v35, v8
	v_pk_mov_b32 v[36:37], v[18:19], v[20:21] op_sel:[1,0]
	v_mov_b32_e32 v8, v11
	v_pk_mov_b32 v[10:11], v[20:21], v[18:19] op_sel:[1,0]
	v_pk_mul_f32 v[18:19], v[48:49], v[12:13] op_sel_hi:[1,0]
	v_pk_mul_f32 v[12:13], v[148:149], v[12:13] op_sel_hi:[1,0]
	v_mov_b32_e32 v26, v9
	v_pk_mul_f32 v[8:9], v[8:9], v[10:11]
	v_pk_mul_f32 v[14:15], v[14:15], v[18:19]
	v_pk_mul_f32 v[16:17], v[16:17], v[12:13]
	v_mov_b32_e32 v12, v22
	v_mov_b32_e32 v13, v25
	v_pk_fma_f32 v[10:11], v[34:35], v[36:37], v[8:9] neg_lo:[0,0,1] neg_hi:[0,0,1]
	v_pk_fma_f32 v[8:9], v[26:27], v[20:21], v[28:29]
	v_pk_mul_f32 v[20:21], v[12:13], v[14:15]
	v_mov_b32_e32 v13, v22
	v_pk_mov_b32 v[26:27], v[14:15], v[16:17] op_sel:[1,0]
	v_mov_b32_e32 v22, v25
	v_pk_mov_b32 v[14:15], v[16:17], v[14:15] op_sel:[1,0]
	v_mov_b32_e32 v18, v23
	v_mov_b32_e32 v19, v24
	v_mov_b32_e32 v12, v24
	v_pk_mul_f32 v[14:15], v[22:23], v[14:15]
	s_nop 0
	v_pk_fma_f32 v[12:13], v[12:13], v[26:27], v[14:15] neg_lo:[0,0,1] neg_hi:[0,0,1]
	v_pk_fma_f32 v[14:15], v[18:19], v[16:17], v[20:21]
	s_and_b64 vcc, exec, s[42:43]
	s_cbranch_vccz .LBB0_832
	s_branch .LBB0_833
